# gmlp_pre: first W_in transpose iteration prefetches later tiles' source lines to L2 via junk-LDS DMA
# baseline (speedup 1.0000x reference)
.LBB0_21:
	s_ashr_i32 s6, s19, 31
	s_lshr_b32 s6, s6, 29
	s_add_i32 s6, s19, s6
	s_ashr_i32 s14, s6, 3
	s_lshl_b32 s22, s14, 6
	v_or_b32_e32 v0, s22, v14
	v_lshl_add_u32 v1, s14, 5, v15
	v_add_u32_e32 v2, 0xfffff800, v0
	v_cmp_gt_i32_e32 vcc, s18, v0
	s_mul_i32 s10, s14, 0xffa00000
	v_add_u32_e32 v6, s10, v23
	v_cndmask_b32_e32 v10, v2, v1, vcc
	v_cmp_lt_i32_e64 s[6:7], -1, v10
	v_lshl_add_u64 v[4:5], v[10:11], 2, s[42:43]
	v_mov_b32_e32 v10, v11
	v_mov_b64_e32 v[0:1], v[10:11]
	v_mov_b64_e32 v[2:3], v[10:11]
	s_waitcnt lgkmcnt(0)
	s_barrier
	s_cmp_lg_u32 s19, s2
	s_cbranch_scc1 .Lcpfa_skip
	v_lshrrev_b32_e32 v56, 8, v181
	v_lshlrev_b32_e32 v56, 8, v56
	v_add_u32_e32 v56, s2, v56
	v_add_u32_e32 v56, 0x100, v56
	v_lshrrev_b32_e32 v57, 3, v56
	v_and_b32_e32 v58, 7, v56
	v_and_b32_e32 v59, 0x7f, v181
	v_lshl_add_u32 v58, v58, 7, v59
	v_bfe_u32 v59, v181, 7, 1
	v_lshlrev_b32_e32 v60, 5, v57
	v_lshl_add_u32 v60, v59, 12, v60
	v_lshlrev_b32_e32 v61, 6, v57
	v_lshl_add_u32 v61, v59, 5, v61
	v_add_u32_e32 v61, 0xfffff800, v61
	v_cmp_gt_u32_e32 vcc, 64, v57
	s_nop 1
	v_cndmask_b32_e32 v60, v61, v60, vcc
	s_movk_i32 s10, 0x1800
	v_mad_u32_u24 v60, v58, s10, v60
	v_lshlrev_b32_e32 v60, 2, v60
	s_mov_b32 m0, 0x24000
	s_nop 0
	global_load_lds_dword v60, s[42:43]
	s_lshr_b32 s10, s2, 4
	s_and_b32 s11, s2, 15
	s_lshl_b32 s11, s11, 7
	s_lshl_b32 s10, s10, 6
	v_and_b32_e32 v58, 0x7f, v181
	v_add_u32_e32 v58, s11, v58
	v_lshlrev_b32_e32 v58, 10, v58
	v_add_u32_e32 v58, s10, v58
	v_lshl_add_u32 v58, v59, 5, v58
	v_lshlrev_b32_e32 v58, 2, v58
	global_load_lds_dword v58, s[60:61]
.Lcpfa_skip:
	s_and_saveexec_b64 s[10:11], s[6:7]
	s_cbranch_execz .LBB0_23
	v_ashrrev_i32_e32 v7, 31, v6
	v_lshl_add_u64 v[0:1], v[6:7], 2, v[4:5]
	global_load_dwordx4 v[0:3], v[0:1], off
	v_add_u32_e32 v56, 0x30000, v6
	v_ashrrev_i32_e32 v57, 31, v56
	v_lshl_add_u64 v[56:57], v[56:57], 2, v[4:5]
	global_load_dwordx4 v[40:43], v[56:57], off
	v_add_u32_e32 v56, 0x60000, v6
	v_ashrrev_i32_e32 v57, 31, v56
	v_lshl_add_u64 v[56:57], v[56:57], 2, v[4:5]
	global_load_dwordx4 v[44:47], v[56:57], off
	v_add_u32_e32 v56, 0x90000, v6
	v_ashrrev_i32_e32 v57, 31, v56
	v_lshl_add_u64 v[56:57], v[56:57], 2, v[4:5]
	global_load_dwordx4 v[48:51], v[56:57], off

.LBB0_1395:
	s_ashr_i32 s4, s17, 31
	s_lshr_b32 s4, s4, 29
	s_add_i32 s4, s17, s4
	s_ashr_i32 s12, s4, 3
	s_lshl_b32 s18, s12, 6
	v_or_b32_e32 v0, s18, v16
	v_lshl_add_u32 v1, s12, 5, v17
	v_add_u32_e32 v2, 0xfffff800, v0
	v_cmp_gt_i32_e32 vcc, s16, v0
	s_mul_i32 s8, s12, 0xffa00000
	v_add_u32_e32 v6, s8, v25
	v_cndmask_b32_e32 v10, v2, v1, vcc
	v_cmp_lt_i32_e64 s[4:5], -1, v10
	v_lshl_add_u64 v[4:5], v[10:11], 2, s[52:53]
	v_mov_b32_e32 v10, v11
	v_mov_b64_e32 v[0:1], v[10:11]
	v_mov_b64_e32 v[2:3], v[10:11]
	s_waitcnt vmcnt(63) expcnt(7) lgkmcnt(15)
	s_barrier
	s_cmp_lg_u32 s17, s2
	s_cbranch_scc1 .Lcpfb_skip
	v_lshrrev_b32_e32 v56, 8, v181
	v_lshlrev_b32_e32 v56, 8, v56
	v_add_u32_e32 v56, s2, v56
	v_add_u32_e32 v56, 0x100, v56
	v_lshrrev_b32_e32 v57, 3, v56
	v_and_b32_e32 v58, 7, v56
	v_and_b32_e32 v59, 0x7f, v181
	v_lshl_add_u32 v58, v58, 7, v59
	v_bfe_u32 v59, v181, 7, 1
	v_lshlrev_b32_e32 v60, 5, v57
	v_lshl_add_u32 v60, v59, 12, v60
	v_lshlrev_b32_e32 v61, 6, v57
	v_lshl_add_u32 v61, v59, 5, v61
	v_add_u32_e32 v61, 0xfffff800, v61
	v_cmp_gt_u32_e32 vcc, 64, v57
	s_nop 1
	v_cndmask_b32_e32 v60, v61, v60, vcc
	s_movk_i32 s8, 0x1800
	v_mad_u32_u24 v60, v58, s8, v60
	v_lshlrev_b32_e32 v60, 2, v60
	s_mov_b32 m0, 0x24000
	s_nop 0
	global_load_lds_dword v60, s[52:53]
	s_lshr_b32 s8, s2, 4
	s_and_b32 s9, s2, 15
	s_lshl_b32 s9, s9, 7
	s_lshl_b32 s8, s8, 6
	v_and_b32_e32 v58, 0x7f, v181
	v_add_u32_e32 v58, s9, v58
	v_lshlrev_b32_e32 v58, 10, v58
	v_add_u32_e32 v58, s8, v58
	v_lshl_add_u32 v58, v59, 5, v58
	v_lshlrev_b32_e32 v58, 2, v58
	global_load_lds_dword v58, s[30:31]
.Lcpfb_skip:
	s_and_saveexec_b64 s[8:9], s[4:5]
	s_cbranch_execz .LBB0_1397
	v_ashrrev_i32_e32 v7, 31, v6
	v_lshl_add_u64 v[0:1], v[6:7], 2, v[4:5]
	global_load_dwordx4 v[0:3], v[0:1], off
	v_add_u32_e32 v56, 0x30000, v6
	v_ashrrev_i32_e32 v57, 31, v56
	v_lshl_add_u64 v[56:57], v[56:57], 2, v[4:5]
	global_load_dwordx4 v[40:43], v[56:57], off
	v_add_u32_e32 v56, 0x60000, v6
	v_ashrrev_i32_e32 v57, 31, v56
	v_lshl_add_u64 v[56:57], v[56:57], 2, v[4:5]
	global_load_dwordx4 v[44:47], v[56:57], off
	v_add_u32_e32 v56, 0x90000, v6
	v_ashrrev_i32_e32 v57, 31, v56
	v_lshl_add_u64 v[56:57], v[56:57], 2, v[4:5]
	global_load_dwordx4 v[48:51], v[56:57], off
